# phase-0 seam uses the XCD grid barrier instead of the cooperative-groups sync (on top of the f12, out-GEMM-epilogue and ph_rec changes)
# speedup vs baseline: 1.0572x; 1.0092x over previous
.LBB0_557:
	v_readlane_b32 s2, v255, 0
	v_readlane_b32 s3, v255, 1
	s_and_b64 vcc, exec, s[2:3]
	s_waitcnt vmcnt(0)
	s_waitcnt vmcnt(0) lgkmcnt(0)
	s_barrier
	s_mov_b64 s[2:3], exec
	v_readlane_b32 s0, v254, 49
	v_readlane_b32 s1, v254, 50
	s_and_b64 s[0:1], s[2:3], s[0:1]
	s_mov_b64 exec, s[0:1]
	s_cbranch_execz .LBB0_607
	v_readlane_b32 s0, v254, 47
	s_waitcnt vmcnt(0) expcnt(0) lgkmcnt(0)
	s_nop 0
	v_mov_b32_e32 v0, s0
	ds_read_b32 v2, v0
	v_readlane_b32 s0, v254, 48
	s_waitcnt lgkmcnt(0)
	v_cmp_ne_u32_e32 vcc, 0, v2
	v_mov_b32_e32 v0, s0
	ds_read_b32 v0, v0
	s_cbranch_vccnz .LBB0_575
	s_mov_b32 s0, 1
	s_branch .LBB0_562
